# QK^T K-fragment ds_reads streamed through 3 buffers with counted lgkmcnt (same MFMA order) on top of the current best
# speedup vs baseline: 1.0010x; 1.0010x over previous
.LBB0_559:
	s_lshl_b32 s20, s4, 6
	s_cmp_lt_i32 s13, s20
	s_cbranch_scc1 .LBB0_574
	s_or_b32 s4, s20, 63
	s_sub_i32 s5, s10, s4
	s_cmpk_gt_i32 s5, 0x80
	s_cbranch_scc1 .LBB0_574
	v_add_u32_e32 v208, v193, v0
	ds_read_b128 v[130:133], v208
	ds_read_b128 v[186:189], v208 offset:64
	ds_read_b128 v[138:141], v208 offset:4608
	ds_read_b128 v[200:203], v208 offset:4672
	ds_read_b128 v[146:149], v208 offset:9216
	ds_read_b128 v[204:207], v208 offset:9280
	ds_read_b128 v[154:157], v208 offset:13824
	s_cmp_lt_i32 s10, s4
	s_cselect_b64 s[4:5], -1, 0
	s_sub_i32 s12, s13, s20
	s_cmpk_gt_i32 s12, 0x80
	s_waitcnt lgkmcnt(6)
	v_mfma_f32_16x16x32_bf16 v[134:137], v[130:133], v[6:9], 0
	s_cselect_b64 s[38:39], -1, 0
	s_or_b64 s[4:5], s[4:5], s[38:39]
	s_mov_b64 s[38:39], -1
	v_mfma_f32_16x16x32_bf16 v[130:133], v[130:133], v[22:25], 0
	s_and_b64 vcc, exec, s[4:5]
	s_waitcnt lgkmcnt(5)
	v_mfma_f32_16x16x32_bf16 v[134:137], v[186:189], v[10:13], v[134:137]
	v_mfma_f32_16x16x32_bf16 v[130:133], v[186:189], v[26:29], v[130:133]
	ds_read_b128 v[186:189], v208 offset:13888
	s_waitcnt lgkmcnt(5)
	v_mfma_f32_16x16x32_bf16 v[142:145], v[138:141], v[6:9], 0
	v_mfma_f32_16x16x32_bf16 v[138:141], v[138:141], v[22:25], 0
	s_waitcnt lgkmcnt(4)
	v_mfma_f32_16x16x32_bf16 v[142:145], v[200:203], v[10:13], v[142:145]
	v_mfma_f32_16x16x32_bf16 v[138:141], v[200:203], v[26:29], v[138:141]
	ds_read_b128 v[200:203], v208 offset:128
	s_waitcnt lgkmcnt(4)
	v_mfma_f32_16x16x32_bf16 v[150:153], v[146:149], v[6:9], 0
	v_mfma_f32_16x16x32_bf16 v[146:149], v[146:149], v[22:25], 0
	s_waitcnt lgkmcnt(3)
	v_mfma_f32_16x16x32_bf16 v[150:153], v[204:207], v[10:13], v[150:153]
	v_mfma_f32_16x16x32_bf16 v[146:149], v[204:207], v[26:29], v[146:149]
	ds_read_b128 v[204:207], v208 offset:4736
	s_waitcnt lgkmcnt(3)
	v_mfma_f32_16x16x32_bf16 v[158:161], v[154:157], v[6:9], 0
	v_mfma_f32_16x16x32_bf16 v[154:157], v[154:157], v[22:25], 0
	s_waitcnt lgkmcnt(2)
	v_mfma_f32_16x16x32_bf16 v[158:161], v[186:189], v[10:13], v[158:161]
	v_mfma_f32_16x16x32_bf16 v[154:157], v[186:189], v[26:29], v[154:157]
	ds_read_b128 v[186:189], v208 offset:9344
	s_waitcnt lgkmcnt(2)
	v_mfma_f32_16x16x32_bf16 v[134:137], v[200:203], v[14:17], v[134:137]
	v_mfma_f32_16x16x32_bf16 v[130:133], v[200:203], v[30:33], v[130:133]
	s_waitcnt lgkmcnt(1)
	v_mfma_f32_16x16x32_bf16 v[142:145], v[204:207], v[14:17], v[142:145]
	v_mfma_f32_16x16x32_bf16 v[138:141], v[204:207], v[30:33], v[138:141]
	s_waitcnt lgkmcnt(0)
	v_mfma_f32_16x16x32_bf16 v[200:203], v[186:189], v[14:17], v[150:153]
	s_nop 2
	ds_read_b128 v[150:153], v208 offset:192
	v_mfma_f32_16x16x32_bf16 v[186:189], v[186:189], v[30:33], v[146:149]
	s_nop 2
	ds_read_b128 v[146:149], v208 offset:13952
	s_waitcnt lgkmcnt(0)
	v_mfma_f32_16x16x32_bf16 v[158:161], v[146:149], v[14:17], v[158:161]
	v_mfma_f32_16x16x32_bf16 v[204:207], v[146:149], v[30:33], v[154:157]
	v_mfma_f32_16x16x32_bf16 v[146:149], v[150:153], v[18:21], v[134:137]
	s_nop 2
	ds_read_b128 v[134:137], v208 offset:4800
	v_mfma_f32_16x16x32_bf16 v[130:133], v[150:153], v[34:37], v[130:133]
	s_waitcnt lgkmcnt(0)
	v_mfma_f32_16x16x32_bf16 v[150:153], v[134:137], v[18:21], v[142:145]
	s_nop 2
	ds_read_b128 v[142:145], v208 offset:14016
	v_mfma_f32_16x16x32_bf16 v[134:137], v[134:137], v[34:37], v[138:141]
	s_nop 2
	ds_read_b128 v[138:141], v208 offset:9408
	s_waitcnt lgkmcnt(0)
	v_mfma_f32_16x16x32_bf16 v[154:157], v[138:141], v[18:21], v[200:203]
	v_mfma_f32_16x16x32_bf16 v[138:141], v[138:141], v[34:37], v[186:189]
	v_mfma_f32_16x16x32_bf16 v[158:161], v[142:145], v[18:21], v[158:161]
	v_mfma_f32_16x16x32_bf16 v[142:145], v[142:145], v[34:37], v[204:207]
	s_cbranch_vccnz .LBB0_563
	v_max_f32_e32 v186, v149, v149
	v_max_f32_e32 v187, v148, v148
	v_max_f32_e32 v186, v187, v186
	v_max_f32_e32 v187, v153, v153
	v_max_f32_e32 v188, v152, v152
	v_max_f32_e32 v187, v188, v187
	v_max3_f32 v186, v146, v147, v186
	v_max3_f32 v187, v150, v151, v187
	v_max3_f32 v186, v186, s88, v187
	v_max_f32_e32 v187, v157, v157
	v_max_f32_e32 v188, v156, v156
	v_max_f32_e32 v187, v188, v187
	v_max_f32_e32 v188, v161, v161
	v_max_f32_e32 v189, v160, v160
	v_max_f32_e32 v188, v189, v188
	v_max3_f32 v187, v154, v155, v187
	v_max3_f32 v188, v158, v159, v188
	v_max3_f32 v200, v186, v187, v188
	s_mov_b64 s[38:39], 0

.LBB0_579:
	s_lshl_b32 s15, s15, 6
	s_cmp_lt_i32 s13, s15
	s_cbranch_scc1 .LBB0_594
	s_or_b32 s4, s15, 63
	s_sub_i32 s5, s10, s4
	s_cmpk_gt_i32 s5, 0x80
	s_cbranch_scc1 .LBB0_594
	v_add_u32_e32 v208, v193, v0
	ds_read_b128 v[130:133], v208 offset:36864
	ds_read_b128 v[186:189], v208 offset:36928
	ds_read_b128 v[138:141], v208 offset:41472
	ds_read_b128 v[200:203], v208 offset:41536
	ds_read_b128 v[146:149], v208 offset:46080
	ds_read_b128 v[204:207], v208 offset:46144
	ds_read_b128 v[154:157], v208 offset:50688
	s_cmp_lt_i32 s10, s4
	s_cselect_b64 s[4:5], -1, 0
	s_sub_i32 s12, s13, s15
	s_cmpk_gt_i32 s12, 0x80
	s_waitcnt lgkmcnt(6)
	v_mfma_f32_16x16x32_bf16 v[134:137], v[130:133], v[6:9], 0
	s_cselect_b64 s[38:39], -1, 0
	s_or_b64 s[4:5], s[4:5], s[38:39]
	s_mov_b64 s[38:39], -1
	v_mfma_f32_16x16x32_bf16 v[130:133], v[130:133], v[22:25], 0
	s_and_b64 vcc, exec, s[4:5]
	s_waitcnt lgkmcnt(5)
	v_mfma_f32_16x16x32_bf16 v[134:137], v[186:189], v[10:13], v[134:137]
	v_mfma_f32_16x16x32_bf16 v[130:133], v[186:189], v[26:29], v[130:133]
	ds_read_b128 v[186:189], v208 offset:50752
	s_waitcnt lgkmcnt(5)
	v_mfma_f32_16x16x32_bf16 v[142:145], v[138:141], v[6:9], 0
	v_mfma_f32_16x16x32_bf16 v[138:141], v[138:141], v[22:25], 0
	s_waitcnt lgkmcnt(4)
	v_mfma_f32_16x16x32_bf16 v[142:145], v[200:203], v[10:13], v[142:145]
	v_mfma_f32_16x16x32_bf16 v[138:141], v[200:203], v[26:29], v[138:141]
	ds_read_b128 v[200:203], v208 offset:36992
	s_waitcnt lgkmcnt(4)
	v_mfma_f32_16x16x32_bf16 v[150:153], v[146:149], v[6:9], 0
	v_mfma_f32_16x16x32_bf16 v[146:149], v[146:149], v[22:25], 0
	s_waitcnt lgkmcnt(3)
	v_mfma_f32_16x16x32_bf16 v[150:153], v[204:207], v[10:13], v[150:153]
	v_mfma_f32_16x16x32_bf16 v[146:149], v[204:207], v[26:29], v[146:149]
	ds_read_b128 v[204:207], v208 offset:41600
	s_waitcnt lgkmcnt(3)
	v_mfma_f32_16x16x32_bf16 v[158:161], v[154:157], v[6:9], 0
	v_mfma_f32_16x16x32_bf16 v[154:157], v[154:157], v[22:25], 0
	s_waitcnt lgkmcnt(2)
	v_mfma_f32_16x16x32_bf16 v[158:161], v[186:189], v[10:13], v[158:161]
	v_mfma_f32_16x16x32_bf16 v[154:157], v[186:189], v[26:29], v[154:157]
	ds_read_b128 v[186:189], v208 offset:46208
	s_waitcnt lgkmcnt(2)
	v_mfma_f32_16x16x32_bf16 v[134:137], v[200:203], v[14:17], v[134:137]
	v_mfma_f32_16x16x32_bf16 v[130:133], v[200:203], v[30:33], v[130:133]
	s_waitcnt lgkmcnt(1)
	v_mfma_f32_16x16x32_bf16 v[142:145], v[204:207], v[14:17], v[142:145]
	v_mfma_f32_16x16x32_bf16 v[138:141], v[204:207], v[30:33], v[138:141]
	s_waitcnt lgkmcnt(0)
	v_mfma_f32_16x16x32_bf16 v[200:203], v[186:189], v[14:17], v[150:153]
	s_nop 2
	ds_read_b128 v[150:153], v208 offset:37056
	v_mfma_f32_16x16x32_bf16 v[186:189], v[186:189], v[30:33], v[146:149]
	s_nop 2
	ds_read_b128 v[146:149], v208 offset:50816
	s_waitcnt lgkmcnt(0)
	v_mfma_f32_16x16x32_bf16 v[158:161], v[146:149], v[14:17], v[158:161]
	v_mfma_f32_16x16x32_bf16 v[204:207], v[146:149], v[30:33], v[154:157]
	v_mfma_f32_16x16x32_bf16 v[146:149], v[150:153], v[18:21], v[134:137]
	s_nop 2
	ds_read_b128 v[134:137], v208 offset:41664
	v_mfma_f32_16x16x32_bf16 v[130:133], v[150:153], v[34:37], v[130:133]
	s_waitcnt lgkmcnt(0)
	v_mfma_f32_16x16x32_bf16 v[150:153], v[134:137], v[18:21], v[142:145]
	s_nop 2
	ds_read_b128 v[142:145], v208 offset:50880
	v_mfma_f32_16x16x32_bf16 v[134:137], v[134:137], v[34:37], v[138:141]
	s_nop 2
	ds_read_b128 v[138:141], v208 offset:46272
	s_waitcnt lgkmcnt(0)
	v_mfma_f32_16x16x32_bf16 v[154:157], v[138:141], v[18:21], v[200:203]
	v_mfma_f32_16x16x32_bf16 v[138:141], v[138:141], v[34:37], v[186:189]
	v_mfma_f32_16x16x32_bf16 v[158:161], v[142:145], v[18:21], v[158:161]
	v_mfma_f32_16x16x32_bf16 v[142:145], v[142:145], v[34:37], v[204:207]
	s_cbranch_vccnz .LBB0_583
	v_max_f32_e32 v186, v149, v149
	v_max_f32_e32 v187, v148, v148
	v_max_f32_e32 v186, v187, v186
	v_max_f32_e32 v187, v153, v153
	v_max_f32_e32 v188, v152, v152
	v_max_f32_e32 v187, v188, v187
	v_max3_f32 v186, v146, v147, v186
	v_max3_f32 v187, v150, v151, v187
	v_max3_f32 v186, v186, s88, v187
	v_max_f32_e32 v187, v157, v157
	v_max_f32_e32 v188, v156, v156
	v_max_f32_e32 v187, v188, v187
	v_max_f32_e32 v188, v161, v161
	v_max_f32_e32 v189, v160, v160
	v_max_f32_e32 v188, v189, v188
	v_max3_f32 v187, v154, v155, v187
	v_max3_f32 v188, v158, v159, v188
	v_max3_f32 v200, v186, v187, v188
	s_mov_b64 s[38:39], 0

.LBB0_609:
	s_lshl_b32 s15, s4, 6
	s_cmp_lt_i32 s10, s15
	s_cbranch_scc1 .LBB0_624
	s_or_b32 s4, s15, 63
	s_sub_i32 s5, s9, s4
	s_cmpk_gt_i32 s5, 0x80
	s_cbranch_scc1 .LBB0_645
	v_add_u32_e32 v164, v198, v162
	ds_read_b128 v[130:133], v164
	ds_read_b128 v[186:189], v164 offset:64
	ds_read_b128 v[138:141], v164 offset:4608
	ds_read_b128 v[204:207], v164 offset:4672
	ds_read_b128 v[146:149], v164 offset:9216
	ds_read_b128 v[218:221], v164 offset:9280
	ds_read_b128 v[154:157], v164 offset:13824
	s_cmp_lt_i32 s9, s4
	s_cselect_b64 s[4:5], -1, 0
	s_sub_i32 s12, s10, s15
	s_cmpk_gt_i32 s12, 0x80
	s_waitcnt lgkmcnt(6)
	v_mfma_f32_16x16x32_bf16 v[134:137], v[130:133], v[18:21], 0
	s_cselect_b64 s[38:39], -1, 0
	s_or_b64 s[4:5], s[4:5], s[38:39]
	s_mov_b64 s[38:39], -1
	v_mfma_f32_16x16x32_bf16 v[130:133], v[130:133], v[34:37], 0
	s_and_b64 vcc, exec, s[4:5]
	s_waitcnt lgkmcnt(5)
	v_mfma_f32_16x16x32_bf16 v[134:137], v[186:189], v[22:25], v[134:137]
	v_mfma_f32_16x16x32_bf16 v[130:133], v[186:189], v[38:41], v[130:133]
	ds_read_b128 v[186:189], v164 offset:13888
	s_waitcnt lgkmcnt(5)
	v_mfma_f32_16x16x32_bf16 v[142:145], v[138:141], v[18:21], 0
	v_mfma_f32_16x16x32_bf16 v[138:141], v[138:141], v[34:37], 0
	s_waitcnt lgkmcnt(4)
	v_mfma_f32_16x16x32_bf16 v[142:145], v[204:207], v[22:25], v[142:145]
	v_mfma_f32_16x16x32_bf16 v[138:141], v[204:207], v[38:41], v[138:141]
	ds_read_b128 v[204:207], v164 offset:128
	s_waitcnt lgkmcnt(4)
	v_mfma_f32_16x16x32_bf16 v[150:153], v[146:149], v[18:21], 0
	v_mfma_f32_16x16x32_bf16 v[146:149], v[146:149], v[34:37], 0
	s_waitcnt lgkmcnt(3)
	v_mfma_f32_16x16x32_bf16 v[150:153], v[218:221], v[22:25], v[150:153]
	v_mfma_f32_16x16x32_bf16 v[146:149], v[218:221], v[38:41], v[146:149]
	ds_read_b128 v[218:221], v164 offset:4736
	s_waitcnt lgkmcnt(3)
	v_mfma_f32_16x16x32_bf16 v[158:161], v[154:157], v[18:21], 0
	v_mfma_f32_16x16x32_bf16 v[154:157], v[154:157], v[34:37], 0
	s_waitcnt lgkmcnt(2)
	v_mfma_f32_16x16x32_bf16 v[158:161], v[186:189], v[22:25], v[158:161]
	v_mfma_f32_16x16x32_bf16 v[154:157], v[186:189], v[38:41], v[154:157]
	ds_read_b128 v[186:189], v164 offset:9344
	s_waitcnt lgkmcnt(2)
	v_mfma_f32_16x16x32_bf16 v[134:137], v[204:207], v[26:29], v[134:137]
	v_mfma_f32_16x16x32_bf16 v[130:133], v[204:207], v[46:49], v[130:133]
	s_waitcnt lgkmcnt(1)
	v_mfma_f32_16x16x32_bf16 v[142:145], v[218:221], v[26:29], v[142:145]
	v_mfma_f32_16x16x32_bf16 v[138:141], v[218:221], v[46:49], v[138:141]
	s_waitcnt lgkmcnt(0)
	v_mfma_f32_16x16x32_bf16 v[204:207], v[186:189], v[26:29], v[150:153]
	s_nop 2
	ds_read_b128 v[150:153], v164 offset:192
	v_mfma_f32_16x16x32_bf16 v[186:189], v[186:189], v[46:49], v[146:149]
	s_nop 2
	ds_read_b128 v[146:149], v164 offset:13952
	s_waitcnt lgkmcnt(0)
	v_mfma_f32_16x16x32_bf16 v[158:161], v[146:149], v[26:29], v[158:161]
	v_mfma_f32_16x16x32_bf16 v[218:221], v[146:149], v[46:49], v[154:157]
	v_mfma_f32_16x16x32_bf16 v[146:149], v[150:153], v[30:33], v[134:137]
	s_nop 2
	ds_read_b128 v[134:137], v164 offset:4800
	v_mfma_f32_16x16x32_bf16 v[130:133], v[150:153], v[50:53], v[130:133]
	s_waitcnt lgkmcnt(0)
	v_mfma_f32_16x16x32_bf16 v[150:153], v[134:137], v[30:33], v[142:145]
	s_nop 2
	ds_read_b128 v[142:145], v164 offset:14016
	v_mfma_f32_16x16x32_bf16 v[134:137], v[134:137], v[50:53], v[138:141]
	s_nop 2
	ds_read_b128 v[138:141], v164 offset:9408
	s_waitcnt lgkmcnt(0)
	v_mfma_f32_16x16x32_bf16 v[154:157], v[138:141], v[30:33], v[204:207]
	v_mfma_f32_16x16x32_bf16 v[138:141], v[138:141], v[50:53], v[186:189]
	v_mfma_f32_16x16x32_bf16 v[158:161], v[142:145], v[30:33], v[158:161]
	v_mfma_f32_16x16x32_bf16 v[142:145], v[142:145], v[50:53], v[218:221]
	s_cbranch_vccnz .LBB0_613
	v_max_f32_e32 v164, v149, v149
	v_max_f32_e32 v165, v148, v148
	v_max_f32_e32 v164, v165, v164
	v_max_f32_e32 v165, v153, v153
	v_max_f32_e32 v168, v152, v152
	v_max_f32_e32 v165, v168, v165
	v_max3_f32 v164, v146, v147, v164
	v_max3_f32 v165, v150, v151, v165
	v_max3_f32 v164, v164, s88, v165
	v_max_f32_e32 v165, v157, v157
	v_max_f32_e32 v168, v156, v156
	v_max_f32_e32 v165, v168, v165
	v_max_f32_e32 v168, v161, v161
	v_max_f32_e32 v169, v160, v160
	v_max_f32_e32 v168, v169, v168
	v_max3_f32 v165, v154, v155, v165
	v_max3_f32 v168, v158, v159, v168
	v_max3_f32 v164, v164, v165, v168
	s_mov_b64 s[38:39], 0

.LBB0_629:
	s_lshl_b32 s14, s14, 6
	s_cmp_lt_i32 s10, s14
	s_cbranch_scc1 .LBB0_646
	s_or_b32 s4, s14, 63
	s_sub_i32 s5, s9, s4
	s_cmpk_gt_i32 s5, 0x80
	s_cbranch_scc1 .LBB0_647
	v_add_u32_e32 v203, v198, v162
	ds_read_b128 v[130:133], v203 offset:36864
	ds_read_b128 v[166:169], v203 offset:36928
	ds_read_b128 v[138:141], v203 offset:41472
	ds_read_b128 v[186:189], v203 offset:41536
	ds_read_b128 v[146:149], v203 offset:46080
	ds_read_b128 v[204:207], v203 offset:46144
	ds_read_b128 v[154:157], v203 offset:50688
	s_cmp_lt_i32 s9, s4
	s_cselect_b64 s[4:5], -1, 0
	s_sub_i32 s12, s10, s14
	s_cmpk_gt_i32 s12, 0x80
	s_waitcnt lgkmcnt(6)
	v_mfma_f32_16x16x32_bf16 v[134:137], v[130:133], v[18:21], 0
	s_cselect_b64 s[38:39], -1, 0
	s_or_b64 s[4:5], s[4:5], s[38:39]
	s_mov_b64 s[38:39], -1
	v_mfma_f32_16x16x32_bf16 v[130:133], v[130:133], v[34:37], 0
	s_and_b64 vcc, exec, s[4:5]
	s_waitcnt lgkmcnt(5)
	v_mfma_f32_16x16x32_bf16 v[134:137], v[166:169], v[22:25], v[134:137]
	v_mfma_f32_16x16x32_bf16 v[130:133], v[166:169], v[38:41], v[130:133]
	ds_read_b128 v[166:169], v203 offset:50752
	s_waitcnt lgkmcnt(5)
	v_mfma_f32_16x16x32_bf16 v[142:145], v[138:141], v[18:21], 0
	v_mfma_f32_16x16x32_bf16 v[138:141], v[138:141], v[34:37], 0
	s_waitcnt lgkmcnt(4)
	v_mfma_f32_16x16x32_bf16 v[142:145], v[186:189], v[22:25], v[142:145]
	v_mfma_f32_16x16x32_bf16 v[138:141], v[186:189], v[38:41], v[138:141]
	ds_read_b128 v[186:189], v203 offset:36992
	s_waitcnt lgkmcnt(4)
	v_mfma_f32_16x16x32_bf16 v[150:153], v[146:149], v[18:21], 0
	v_mfma_f32_16x16x32_bf16 v[146:149], v[146:149], v[34:37], 0
	s_waitcnt lgkmcnt(3)
	v_mfma_f32_16x16x32_bf16 v[150:153], v[204:207], v[22:25], v[150:153]
	v_mfma_f32_16x16x32_bf16 v[146:149], v[204:207], v[38:41], v[146:149]
	ds_read_b128 v[204:207], v203 offset:41600
	s_waitcnt lgkmcnt(3)
	v_mfma_f32_16x16x32_bf16 v[158:161], v[154:157], v[18:21], 0
	v_mfma_f32_16x16x32_bf16 v[154:157], v[154:157], v[34:37], 0
	s_waitcnt lgkmcnt(2)
	v_mfma_f32_16x16x32_bf16 v[158:161], v[166:169], v[22:25], v[158:161]
	v_mfma_f32_16x16x32_bf16 v[154:157], v[166:169], v[38:41], v[154:157]
	ds_read_b128 v[166:169], v203 offset:46208
	s_waitcnt lgkmcnt(2)
	v_mfma_f32_16x16x32_bf16 v[134:137], v[186:189], v[26:29], v[134:137]
	v_mfma_f32_16x16x32_bf16 v[130:133], v[186:189], v[46:49], v[130:133]
	s_waitcnt lgkmcnt(1)
	v_mfma_f32_16x16x32_bf16 v[142:145], v[204:207], v[26:29], v[142:145]
	v_mfma_f32_16x16x32_bf16 v[138:141], v[204:207], v[46:49], v[138:141]
	s_waitcnt lgkmcnt(0)
	v_mfma_f32_16x16x32_bf16 v[186:189], v[166:169], v[26:29], v[150:153]
	s_nop 2
	ds_read_b128 v[150:153], v203 offset:37056
	v_mfma_f32_16x16x32_bf16 v[166:169], v[166:169], v[46:49], v[146:149]
	s_nop 2
	ds_read_b128 v[146:149], v203 offset:50816
	s_waitcnt lgkmcnt(0)
	v_mfma_f32_16x16x32_bf16 v[158:161], v[146:149], v[26:29], v[158:161]
	v_mfma_f32_16x16x32_bf16 v[204:207], v[146:149], v[46:49], v[154:157]
	v_mfma_f32_16x16x32_bf16 v[146:149], v[150:153], v[30:33], v[134:137]
	s_nop 2
	ds_read_b128 v[134:137], v203 offset:41664
	v_mfma_f32_16x16x32_bf16 v[130:133], v[150:153], v[50:53], v[130:133]
	s_waitcnt lgkmcnt(0)
	v_mfma_f32_16x16x32_bf16 v[150:153], v[134:137], v[30:33], v[142:145]
	s_nop 2
	ds_read_b128 v[142:145], v203 offset:50880
	v_mfma_f32_16x16x32_bf16 v[134:137], v[134:137], v[50:53], v[138:141]
	s_nop 2
	ds_read_b128 v[138:141], v203 offset:46272
	s_waitcnt lgkmcnt(0)
	v_mfma_f32_16x16x32_bf16 v[154:157], v[138:141], v[30:33], v[186:189]
	v_mfma_f32_16x16x32_bf16 v[138:141], v[138:141], v[50:53], v[166:169]
	v_mfma_f32_16x16x32_bf16 v[158:161], v[142:145], v[30:33], v[158:161]
	v_mfma_f32_16x16x32_bf16 v[142:145], v[142:145], v[50:53], v[204:207]
	s_cbranch_vccnz .LBB0_633
	v_max_f32_e32 v166, v149, v149
	v_max_f32_e32 v167, v148, v148
	v_max_f32_e32 v166, v167, v166
	v_max_f32_e32 v167, v153, v153
	v_max_f32_e32 v168, v152, v152
	v_max_f32_e32 v167, v168, v167
	v_max3_f32 v166, v146, v147, v166
	v_max3_f32 v167, v150, v151, v167
	v_max3_f32 v166, v166, s88, v167
	v_max_f32_e32 v167, v157, v157
	v_max_f32_e32 v168, v156, v156
	v_max_f32_e32 v167, v168, v167
	v_max_f32_e32 v168, v161, v161
	v_max_f32_e32 v169, v160, v160
	v_max_f32_e32 v168, v169, v168
	v_max3_f32 v167, v154, v155, v167
	v_max3_f32 v168, v158, v159, v168
	v_max3_f32 v166, v166, v167, v168
	s_mov_b64 s[38:39], 0

.LBB0_830:
	s_or_b32 s12, s44, 63
	s_sub_i32 s45, s26, s12
	s_cmp_lt_i32 s45, s27
	s_cselect_b64 s[52:53], -1, 0
	s_and_b64 s[4:5], s[52:53], s[4:5]
	s_andn2_b64 vcc, exec, s[4:5]
	s_cbranch_vccnz .LBB0_844
	v_add_u32_e32 v236, v209, v0
	ds_read_b128 v[132:135], v236
	ds_read_b128 v[186:189], v236 offset:64
	ds_read_b128 v[140:143], v236 offset:4608
	ds_read_b128 v[218:221], v236 offset:4672
	ds_read_b128 v[148:151], v236 offset:9216
	ds_read_b128 v[222:225], v236 offset:9280
	ds_read_b128 v[156:159], v236 offset:13824
	s_cmp_lt_i32 s26, s12
	s_cselect_b64 s[52:53], -1, 0
	s_sub_i32 s4, s57, s44
	s_cmp_ge_i32 s4, s27
	s_waitcnt lgkmcnt(6)
	v_mfma_f32_16x16x32_bf16 v[136:139], v[132:135], v[8:11], 0
	s_cselect_b64 s[4:5], -1, 0
	s_mov_b64 s[38:39], s[52:53]
	s_or_b64 s[4:5], s[38:39], s[4:5]
	v_mfma_f32_16x16x32_bf16 v[132:135], v[132:135], v[24:27], 0
	s_mov_b64 s[38:39], -1
	s_and_b64 vcc, exec, s[4:5]
	s_waitcnt lgkmcnt(5)
	v_mfma_f32_16x16x32_bf16 v[136:139], v[186:189], v[12:15], v[136:139]
	v_mfma_f32_16x16x32_bf16 v[132:135], v[186:189], v[28:31], v[132:135]
	ds_read_b128 v[186:189], v236 offset:13888
	s_waitcnt lgkmcnt(5)
	v_mfma_f32_16x16x32_bf16 v[144:147], v[140:143], v[8:11], 0
	v_mfma_f32_16x16x32_bf16 v[140:143], v[140:143], v[24:27], 0
	s_waitcnt lgkmcnt(4)
	v_mfma_f32_16x16x32_bf16 v[144:147], v[218:221], v[12:15], v[144:147]
	v_mfma_f32_16x16x32_bf16 v[140:143], v[218:221], v[28:31], v[140:143]
	ds_read_b128 v[218:221], v236 offset:128
	s_waitcnt lgkmcnt(4)
	v_mfma_f32_16x16x32_bf16 v[152:155], v[148:151], v[8:11], 0
	v_mfma_f32_16x16x32_bf16 v[148:151], v[148:151], v[24:27], 0
	s_waitcnt lgkmcnt(3)
	v_mfma_f32_16x16x32_bf16 v[152:155], v[222:225], v[12:15], v[152:155]
	v_mfma_f32_16x16x32_bf16 v[148:151], v[222:225], v[28:31], v[148:151]
	ds_read_b128 v[222:225], v236 offset:4736
	s_waitcnt lgkmcnt(3)
	v_mfma_f32_16x16x32_bf16 v[160:163], v[156:159], v[8:11], 0
	v_mfma_f32_16x16x32_bf16 v[156:159], v[156:159], v[24:27], 0
	s_waitcnt lgkmcnt(2)
	v_mfma_f32_16x16x32_bf16 v[160:163], v[186:189], v[12:15], v[160:163]
	v_mfma_f32_16x16x32_bf16 v[156:159], v[186:189], v[28:31], v[156:159]
	ds_read_b128 v[186:189], v236 offset:9344
	s_waitcnt lgkmcnt(2)
	v_mfma_f32_16x16x32_bf16 v[136:139], v[218:221], v[16:19], v[136:139]
	v_mfma_f32_16x16x32_bf16 v[132:135], v[218:221], v[32:35], v[132:135]
	s_waitcnt lgkmcnt(1)
	v_mfma_f32_16x16x32_bf16 v[144:147], v[222:225], v[16:19], v[144:147]
	v_mfma_f32_16x16x32_bf16 v[140:143], v[222:225], v[32:35], v[140:143]
	s_waitcnt lgkmcnt(0)
	v_mfma_f32_16x16x32_bf16 v[218:221], v[186:189], v[16:19], v[152:155]
	s_nop 2
	ds_read_b128 v[152:155], v236 offset:192
	v_mfma_f32_16x16x32_bf16 v[186:189], v[186:189], v[32:35], v[148:151]
	s_nop 2
	ds_read_b128 v[148:151], v236 offset:13952
	s_waitcnt lgkmcnt(0)
	v_mfma_f32_16x16x32_bf16 v[160:163], v[148:151], v[16:19], v[160:163]
	v_mfma_f32_16x16x32_bf16 v[222:225], v[148:151], v[32:35], v[156:159]
	v_mfma_f32_16x16x32_bf16 v[148:151], v[152:155], v[20:23], v[136:139]
	s_nop 2
	ds_read_b128 v[136:139], v236 offset:4800
	v_mfma_f32_16x16x32_bf16 v[132:135], v[152:155], v[36:39], v[132:135]
	s_waitcnt lgkmcnt(0)
	v_mfma_f32_16x16x32_bf16 v[152:155], v[136:139], v[20:23], v[144:147]
	s_nop 2
	ds_read_b128 v[144:147], v236 offset:14016
	v_mfma_f32_16x16x32_bf16 v[136:139], v[136:139], v[36:39], v[140:143]
	s_nop 2
	ds_read_b128 v[140:143], v236 offset:9408
	s_waitcnt lgkmcnt(0)
	v_mfma_f32_16x16x32_bf16 v[156:159], v[140:143], v[20:23], v[218:221]
	v_mfma_f32_16x16x32_bf16 v[140:143], v[140:143], v[36:39], v[186:189]
	v_mfma_f32_16x16x32_bf16 v[160:163], v[144:147], v[20:23], v[160:163]
	v_mfma_f32_16x16x32_bf16 v[144:147], v[144:147], v[36:39], v[222:225]
	s_cbranch_vccnz .LBB0_833
	v_max_f32_e32 v186, v151, v151
	v_max_f32_e32 v187, v150, v150
	v_max_f32_e32 v186, v187, v186
	v_max_f32_e32 v187, v155, v155
	v_max_f32_e32 v188, v154, v154
	v_max_f32_e32 v187, v188, v187
	v_max3_f32 v186, v148, v149, v186
	v_max3_f32 v187, v152, v153, v187
	v_max3_f32 v186, v186, s88, v187
	v_max_f32_e32 v187, v159, v159
	v_max_f32_e32 v188, v158, v158
	v_max_f32_e32 v187, v188, v187
	v_max_f32_e32 v188, v163, v163
	v_max_f32_e32 v189, v162, v162
	v_max_f32_e32 v188, v189, v188
	v_max3_f32 v187, v156, v157, v187
	v_max3_f32 v188, v160, v161, v188
	v_max3_f32 v236, v186, v187, v188
	v_mov_b32_e32 v237, 0x7f800000
	s_andn2_b64 vcc, exec, s[40:41]
	s_cbranch_vccnz .Lrs_nsa_0_0
	v_lshrrev_b32_e32 v238, s68, v179
	v_lshlrev_b32_e32 v238, 31, v238
	v_xor_b32_e32 v237, v238, v228
	v_min_f32_e32 v236, v236, v237

.LBB0_868:
	s_or_b32 s12, s42, 63
	s_sub_i32 s43, s26, s12
	s_cmp_lt_i32 s43, s27
	s_cselect_b64 s[50:51], -1, 0
	s_and_b64 s[4:5], s[50:51], s[4:5]
	s_andn2_b64 vcc, exec, s[4:5]
	s_cbranch_vccnz .LBB0_882
	v_add_u32_e32 v236, v209, v0
	ds_read_b128 v[132:135], v236 offset:36864
	ds_read_b128 v[186:189], v236 offset:36928
	ds_read_b128 v[140:143], v236 offset:41472
	ds_read_b128 v[218:221], v236 offset:41536
	ds_read_b128 v[148:151], v236 offset:46080
	ds_read_b128 v[222:225], v236 offset:46144
	ds_read_b128 v[156:159], v236 offset:50688
	s_cmp_lt_i32 s26, s12
	s_cselect_b64 s[50:51], -1, 0
	s_sub_i32 s4, s57, s42
	s_cmp_ge_i32 s4, s27
	s_waitcnt lgkmcnt(6)
	v_mfma_f32_16x16x32_bf16 v[136:139], v[132:135], v[8:11], 0
	s_cselect_b64 s[4:5], -1, 0
	s_mov_b64 s[38:39], s[50:51]
	s_or_b64 s[4:5], s[38:39], s[4:5]
	v_mfma_f32_16x16x32_bf16 v[132:135], v[132:135], v[24:27], 0
	s_mov_b64 s[38:39], -1
	s_and_b64 vcc, exec, s[4:5]
	s_waitcnt lgkmcnt(5)
	v_mfma_f32_16x16x32_bf16 v[136:139], v[186:189], v[12:15], v[136:139]
	v_mfma_f32_16x16x32_bf16 v[132:135], v[186:189], v[28:31], v[132:135]
	ds_read_b128 v[186:189], v236 offset:50752
	s_waitcnt lgkmcnt(5)
	v_mfma_f32_16x16x32_bf16 v[144:147], v[140:143], v[8:11], 0
	v_mfma_f32_16x16x32_bf16 v[140:143], v[140:143], v[24:27], 0
	s_waitcnt lgkmcnt(4)
	v_mfma_f32_16x16x32_bf16 v[144:147], v[218:221], v[12:15], v[144:147]
	v_mfma_f32_16x16x32_bf16 v[140:143], v[218:221], v[28:31], v[140:143]
	ds_read_b128 v[218:221], v236 offset:36992
	s_waitcnt lgkmcnt(4)
	v_mfma_f32_16x16x32_bf16 v[152:155], v[148:151], v[8:11], 0
	v_mfma_f32_16x16x32_bf16 v[148:151], v[148:151], v[24:27], 0
	s_waitcnt lgkmcnt(3)
	v_mfma_f32_16x16x32_bf16 v[152:155], v[222:225], v[12:15], v[152:155]
	v_mfma_f32_16x16x32_bf16 v[148:151], v[222:225], v[28:31], v[148:151]
	ds_read_b128 v[222:225], v236 offset:41600
	s_waitcnt lgkmcnt(3)
	v_mfma_f32_16x16x32_bf16 v[160:163], v[156:159], v[8:11], 0
	v_mfma_f32_16x16x32_bf16 v[156:159], v[156:159], v[24:27], 0
	s_waitcnt lgkmcnt(2)
	v_mfma_f32_16x16x32_bf16 v[160:163], v[186:189], v[12:15], v[160:163]
	v_mfma_f32_16x16x32_bf16 v[156:159], v[186:189], v[28:31], v[156:159]
	ds_read_b128 v[186:189], v236 offset:46208
	s_waitcnt lgkmcnt(2)
	v_mfma_f32_16x16x32_bf16 v[136:139], v[218:221], v[16:19], v[136:139]
	v_mfma_f32_16x16x32_bf16 v[132:135], v[218:221], v[32:35], v[132:135]
	s_waitcnt lgkmcnt(1)
	v_mfma_f32_16x16x32_bf16 v[144:147], v[222:225], v[16:19], v[144:147]
	v_mfma_f32_16x16x32_bf16 v[140:143], v[222:225], v[32:35], v[140:143]
	s_waitcnt lgkmcnt(0)
	v_mfma_f32_16x16x32_bf16 v[218:221], v[186:189], v[16:19], v[152:155]
	s_nop 2
	ds_read_b128 v[152:155], v236 offset:37056
	v_mfma_f32_16x16x32_bf16 v[186:189], v[186:189], v[32:35], v[148:151]
	s_nop 2
	ds_read_b128 v[148:151], v236 offset:50816
	s_waitcnt lgkmcnt(0)
	v_mfma_f32_16x16x32_bf16 v[160:163], v[148:151], v[16:19], v[160:163]
	v_mfma_f32_16x16x32_bf16 v[222:225], v[148:151], v[32:35], v[156:159]
	v_mfma_f32_16x16x32_bf16 v[148:151], v[152:155], v[20:23], v[136:139]
	s_nop 2
	ds_read_b128 v[136:139], v236 offset:41664
	v_mfma_f32_16x16x32_bf16 v[132:135], v[152:155], v[36:39], v[132:135]
	s_waitcnt lgkmcnt(0)
	v_mfma_f32_16x16x32_bf16 v[152:155], v[136:139], v[20:23], v[144:147]
	s_nop 2
	ds_read_b128 v[144:147], v236 offset:50880
	v_mfma_f32_16x16x32_bf16 v[136:139], v[136:139], v[36:39], v[140:143]
	s_nop 2
	ds_read_b128 v[140:143], v236 offset:46272
	s_waitcnt lgkmcnt(0)
	v_mfma_f32_16x16x32_bf16 v[156:159], v[140:143], v[20:23], v[218:221]
	v_mfma_f32_16x16x32_bf16 v[140:143], v[140:143], v[36:39], v[186:189]
	v_mfma_f32_16x16x32_bf16 v[160:163], v[144:147], v[20:23], v[160:163]
	v_mfma_f32_16x16x32_bf16 v[144:147], v[144:147], v[36:39], v[222:225]
	s_cbranch_vccnz .LBB0_871
	v_max_f32_e32 v186, v151, v151
	v_max_f32_e32 v187, v150, v150
	v_max_f32_e32 v186, v187, v186
	v_max_f32_e32 v187, v155, v155
	v_max_f32_e32 v188, v154, v154
	v_max_f32_e32 v187, v188, v187
	v_max3_f32 v186, v148, v149, v186
	v_max3_f32 v187, v152, v153, v187
	v_max3_f32 v186, v186, s88, v187
	v_max_f32_e32 v187, v159, v159
	v_max_f32_e32 v188, v158, v158
	v_max_f32_e32 v187, v188, v187
	v_max_f32_e32 v188, v163, v163
	v_max_f32_e32 v189, v162, v162
	v_max_f32_e32 v188, v189, v188
	v_max3_f32 v187, v156, v157, v187
	v_max3_f32 v188, v160, v161, v188
	v_max3_f32 v236, v186, v187, v188
	v_mov_b32_e32 v237, 0x7f800000
	s_andn2_b64 vcc, exec, s[40:41]
	s_cbranch_vccnz .Lrs_nsa_1_0
	v_lshrrev_b32_e32 v238, s56, v179
	v_lshlrev_b32_e32 v238, 31, v238
	v_xor_b32_e32 v237, v238, v228
	v_min_f32_e32 v236, v236, v237

.LBB0_991:
	s_ashr_i32 s4, s62, 2
	s_lshl_b32 s4, 1, s4
	v_and_b32_e32 v201, s4, v166
	v_and_b32_e32 v200, s4, v167
	v_cmp_eq_u32_e64 s[40:41], 0, v201
	v_cmp_eq_u32_e64 s[42:43], 0, v200
	v_bitop3_b32 v130, s4, v167, v166 bitop3:0xe0
	s_or_b64 s[4:5], s[40:41], s[42:43]
	s_lshl_b32 s28, s62, 6
	v_cmp_ne_u32_e32 vcc, 0, v130
	v_cndmask_b32_e64 v130, 0, 1, s[4:5]
	s_cmp_lt_i32 s26, s28
	v_cmp_ne_u32_e64 s[40:41], 0, v130
	s_cbranch_scc1 .LBB0_1006
	s_cmp_lg_u64 vcc, 0
	s_cselect_b64 s[38:39], -1, 0
	s_or_b32 s4, s28, 63
	s_sub_i32 s5, s21, s4
	s_cmp_lt_i32 s5, 2.0
	s_cselect_b64 s[42:43], -1, 0
	s_and_b64 s[38:39], s[42:43], s[38:39]
	s_andn2_b64 vcc, exec, s[38:39]
	s_cbranch_vccnz .LBB0_1006
	v_add_u32_e32 v218, v193, v162
	ds_read_b128 v[130:133], v218
	ds_read_b128 v[186:189], v218 offset:64
	ds_read_b128 v[138:141], v218 offset:4608
	ds_read_b128 v[202:205], v218 offset:4672
	ds_read_b128 v[146:149], v218 offset:9216
	ds_read_b128 v[206:209], v218 offset:9280
	ds_read_b128 v[154:157], v218 offset:13824
	s_cmp_lg_u64 s[40:41], 0
	s_cselect_b64 s[38:39], -1, 0
	s_cmp_lt_i32 s21, s4
	s_cselect_b64 s[40:41], -1, 0
	s_waitcnt lgkmcnt(6)
	v_mfma_f32_16x16x32_bf16 v[134:137], v[130:133], v[2:5], 0
	s_sub_i32 s4, s26, s28
	s_cmp_gt_i32 s4, 0x3fffffff
	s_cselect_b64 s[4:5], -1, 0
	v_mfma_f32_16x16x32_bf16 v[130:133], v[130:133], v[18:21], 0
	s_mov_b64 s[38:39], s[40:41]
	s_or_b64 s[4:5], s[38:39], s[4:5]
	s_mov_b64 s[38:39], -1
	s_waitcnt lgkmcnt(5)
	v_mfma_f32_16x16x32_bf16 v[134:137], v[186:189], v[6:9], v[134:137]
	s_and_b64 vcc, exec, s[4:5]
	v_mfma_f32_16x16x32_bf16 v[130:133], v[186:189], v[22:25], v[130:133]
	ds_read_b128 v[186:189], v218 offset:13888
	s_waitcnt lgkmcnt(5)
	v_mfma_f32_16x16x32_bf16 v[142:145], v[138:141], v[2:5], 0
	v_mfma_f32_16x16x32_bf16 v[138:141], v[138:141], v[18:21], 0
	s_waitcnt lgkmcnt(4)
	v_mfma_f32_16x16x32_bf16 v[142:145], v[202:205], v[6:9], v[142:145]
	v_mfma_f32_16x16x32_bf16 v[138:141], v[202:205], v[22:25], v[138:141]
	ds_read_b128 v[202:205], v218 offset:128
	s_waitcnt lgkmcnt(4)
	v_mfma_f32_16x16x32_bf16 v[150:153], v[146:149], v[2:5], 0
	v_mfma_f32_16x16x32_bf16 v[146:149], v[146:149], v[18:21], 0
	s_waitcnt lgkmcnt(3)
	v_mfma_f32_16x16x32_bf16 v[150:153], v[206:209], v[6:9], v[150:153]
	v_mfma_f32_16x16x32_bf16 v[146:149], v[206:209], v[22:25], v[146:149]
	ds_read_b128 v[206:209], v218 offset:4736
	s_waitcnt lgkmcnt(3)
	v_mfma_f32_16x16x32_bf16 v[158:161], v[154:157], v[2:5], 0
	v_mfma_f32_16x16x32_bf16 v[154:157], v[154:157], v[18:21], 0
	s_waitcnt lgkmcnt(2)
	v_mfma_f32_16x16x32_bf16 v[158:161], v[186:189], v[6:9], v[158:161]
	v_mfma_f32_16x16x32_bf16 v[154:157], v[186:189], v[22:25], v[154:157]
	ds_read_b128 v[186:189], v218 offset:9344
	s_waitcnt lgkmcnt(2)
	v_mfma_f32_16x16x32_bf16 v[134:137], v[202:205], v[10:13], v[134:137]
	v_mfma_f32_16x16x32_bf16 v[130:133], v[202:205], v[26:29], v[130:133]
	s_waitcnt lgkmcnt(1)
	v_mfma_f32_16x16x32_bf16 v[142:145], v[206:209], v[10:13], v[142:145]
	v_mfma_f32_16x16x32_bf16 v[138:141], v[206:209], v[26:29], v[138:141]
	s_waitcnt lgkmcnt(0)
	v_mfma_f32_16x16x32_bf16 v[202:205], v[186:189], v[10:13], v[150:153]
	s_nop 2
	ds_read_b128 v[150:153], v218 offset:192
	v_mfma_f32_16x16x32_bf16 v[186:189], v[186:189], v[26:29], v[146:149]
	s_nop 2
	ds_read_b128 v[146:149], v218 offset:13952
	s_waitcnt lgkmcnt(0)
	v_mfma_f32_16x16x32_bf16 v[158:161], v[146:149], v[10:13], v[158:161]
	v_mfma_f32_16x16x32_bf16 v[206:209], v[146:149], v[26:29], v[154:157]
	v_mfma_f32_16x16x32_bf16 v[146:149], v[150:153], v[14:17], v[134:137]
	s_nop 2
	ds_read_b128 v[134:137], v218 offset:4800
	v_mfma_f32_16x16x32_bf16 v[130:133], v[150:153], v[30:33], v[130:133]
	s_waitcnt lgkmcnt(0)
	v_mfma_f32_16x16x32_bf16 v[150:153], v[134:137], v[14:17], v[142:145]
	s_nop 2
	ds_read_b128 v[142:145], v218 offset:14016
	v_mfma_f32_16x16x32_bf16 v[134:137], v[134:137], v[30:33], v[138:141]
	s_nop 2
	ds_read_b128 v[138:141], v218 offset:9408
	s_waitcnt lgkmcnt(0)
	v_mfma_f32_16x16x32_bf16 v[154:157], v[138:141], v[14:17], v[202:205]
	v_mfma_f32_16x16x32_bf16 v[138:141], v[138:141], v[30:33], v[186:189]
	v_mfma_f32_16x16x32_bf16 v[158:161], v[142:145], v[14:17], v[158:161]
	v_mfma_f32_16x16x32_bf16 v[142:145], v[142:145], v[30:33], v[206:209]
	s_cbranch_vccnz .LBB0_995
	v_max_f32_e32 v186, v149, v149
	v_max_f32_e32 v187, v148, v148
	v_max_f32_e32 v186, v187, v186
	v_max_f32_e32 v187, v153, v153
	v_max_f32_e32 v188, v152, v152
	v_max_f32_e32 v187, v188, v187
	v_max3_f32 v186, v146, v147, v186
	v_max3_f32 v187, v150, v151, v187
	v_max3_f32 v186, v186, s88, v187
	v_max_f32_e32 v187, v157, v157
	v_max_f32_e32 v188, v156, v156
	v_max_f32_e32 v187, v188, v187
	v_max_f32_e32 v188, v161, v161
	v_max_f32_e32 v189, v160, v160
	v_max_f32_e32 v188, v189, v188
	v_max3_f32 v187, v154, v155, v187
	v_max3_f32 v188, v158, v159, v188
	v_max3_f32 v202, v186, v187, v188
	v_cmp_eq_u32_e32 vcc, 0, v201
	v_mov_b32_e32 v203, 0x7f800000
	s_nop 1
	v_cndmask_b32_e32 v203, v203, v228, vcc
	v_min_f32_e32 v202, v202, v203
	s_mov_b64 s[38:39], 0

.LBB0_1027:
	s_ashr_i32 s4, s64, 2
	s_lshl_b32 s4, 1, s4
	v_and_b32_e32 v201, s4, v166
	v_and_b32_e32 v200, s4, v167
	v_cmp_eq_u32_e64 s[42:43], 0, v201
	v_cmp_eq_u32_e64 s[44:45], 0, v200
	v_bitop3_b32 v130, s4, v167, v166 bitop3:0xe0
	s_or_b64 s[4:5], s[42:43], s[44:45]
	s_lshl_b32 s28, s64, 6
	v_cmp_ne_u32_e32 vcc, 0, v130
	v_cndmask_b32_e64 v130, 0, 1, s[4:5]
	s_cmp_lt_i32 s26, s28
	v_cmp_ne_u32_e64 s[42:43], 0, v130
	s_cbranch_scc1 .LBB0_1042
	s_cmp_lg_u64 vcc, 0
	s_cselect_b64 s[38:39], -1, 0
	s_or_b32 s4, s28, 63
	s_sub_i32 s5, s21, s4
	s_cmp_lt_i32 s5, 2.0
	s_cselect_b64 s[44:45], -1, 0
	s_and_b64 s[38:39], s[44:45], s[38:39]
	s_andn2_b64 vcc, exec, s[38:39]
	s_cbranch_vccnz .LBB0_1042
	v_add_u32_e32 v218, v193, v162
	ds_read_b128 v[130:133], v218 offset:36864
	ds_read_b128 v[186:189], v218 offset:36928
	ds_read_b128 v[138:141], v218 offset:41472
	ds_read_b128 v[202:205], v218 offset:41536
	ds_read_b128 v[146:149], v218 offset:46080
	ds_read_b128 v[206:209], v218 offset:46144
	ds_read_b128 v[154:157], v218 offset:50688
	s_cmp_lg_u64 s[42:43], 0
	s_cselect_b64 s[38:39], -1, 0
	s_cmp_lt_i32 s21, s4
	s_cselect_b64 s[42:43], -1, 0
	s_waitcnt lgkmcnt(6)
	v_mfma_f32_16x16x32_bf16 v[134:137], v[130:133], v[2:5], 0
	s_sub_i32 s4, s26, s28
	s_cmp_gt_i32 s4, 0x3fffffff
	s_cselect_b64 s[4:5], -1, 0
	v_mfma_f32_16x16x32_bf16 v[130:133], v[130:133], v[18:21], 0
	s_mov_b64 s[38:39], s[42:43]
	s_or_b64 s[4:5], s[38:39], s[4:5]
	s_mov_b64 s[38:39], -1
	s_waitcnt lgkmcnt(5)
	v_mfma_f32_16x16x32_bf16 v[134:137], v[186:189], v[6:9], v[134:137]
	s_and_b64 vcc, exec, s[4:5]
	v_mfma_f32_16x16x32_bf16 v[130:133], v[186:189], v[22:25], v[130:133]
	ds_read_b128 v[186:189], v218 offset:50752
	s_waitcnt lgkmcnt(5)
	v_mfma_f32_16x16x32_bf16 v[142:145], v[138:141], v[2:5], 0
	v_mfma_f32_16x16x32_bf16 v[138:141], v[138:141], v[18:21], 0
	s_waitcnt lgkmcnt(4)
	v_mfma_f32_16x16x32_bf16 v[142:145], v[202:205], v[6:9], v[142:145]
	v_mfma_f32_16x16x32_bf16 v[138:141], v[202:205], v[22:25], v[138:141]
	ds_read_b128 v[202:205], v218 offset:36992
	s_waitcnt lgkmcnt(4)
	v_mfma_f32_16x16x32_bf16 v[150:153], v[146:149], v[2:5], 0
	v_mfma_f32_16x16x32_bf16 v[146:149], v[146:149], v[18:21], 0
	s_waitcnt lgkmcnt(3)
	v_mfma_f32_16x16x32_bf16 v[150:153], v[206:209], v[6:9], v[150:153]
	v_mfma_f32_16x16x32_bf16 v[146:149], v[206:209], v[22:25], v[146:149]
	ds_read_b128 v[206:209], v218 offset:41600
	s_waitcnt lgkmcnt(3)
	v_mfma_f32_16x16x32_bf16 v[158:161], v[154:157], v[2:5], 0
	v_mfma_f32_16x16x32_bf16 v[154:157], v[154:157], v[18:21], 0
	s_waitcnt lgkmcnt(2)
	v_mfma_f32_16x16x32_bf16 v[158:161], v[186:189], v[6:9], v[158:161]
	v_mfma_f32_16x16x32_bf16 v[154:157], v[186:189], v[22:25], v[154:157]
	ds_read_b128 v[186:189], v218 offset:46208
	s_waitcnt lgkmcnt(2)
	v_mfma_f32_16x16x32_bf16 v[134:137], v[202:205], v[10:13], v[134:137]
	v_mfma_f32_16x16x32_bf16 v[130:133], v[202:205], v[26:29], v[130:133]
	s_waitcnt lgkmcnt(1)
	v_mfma_f32_16x16x32_bf16 v[142:145], v[206:209], v[10:13], v[142:145]
	v_mfma_f32_16x16x32_bf16 v[138:141], v[206:209], v[26:29], v[138:141]
	s_waitcnt lgkmcnt(0)
	v_mfma_f32_16x16x32_bf16 v[202:205], v[186:189], v[10:13], v[150:153]
	s_nop 2
	ds_read_b128 v[150:153], v218 offset:37056
	v_mfma_f32_16x16x32_bf16 v[186:189], v[186:189], v[26:29], v[146:149]
	s_nop 2
	ds_read_b128 v[146:149], v218 offset:50816
	s_waitcnt lgkmcnt(0)
	v_mfma_f32_16x16x32_bf16 v[158:161], v[146:149], v[10:13], v[158:161]
	v_mfma_f32_16x16x32_bf16 v[206:209], v[146:149], v[26:29], v[154:157]
	v_mfma_f32_16x16x32_bf16 v[146:149], v[150:153], v[14:17], v[134:137]
	s_nop 2
	ds_read_b128 v[134:137], v218 offset:41664
	v_mfma_f32_16x16x32_bf16 v[130:133], v[150:153], v[30:33], v[130:133]
	s_waitcnt lgkmcnt(0)
	v_mfma_f32_16x16x32_bf16 v[150:153], v[134:137], v[14:17], v[142:145]
	s_nop 2
	ds_read_b128 v[142:145], v218 offset:50880
	v_mfma_f32_16x16x32_bf16 v[134:137], v[134:137], v[30:33], v[138:141]
	s_nop 2
	ds_read_b128 v[138:141], v218 offset:46272
	s_waitcnt lgkmcnt(0)
	v_mfma_f32_16x16x32_bf16 v[154:157], v[138:141], v[14:17], v[202:205]
	v_mfma_f32_16x16x32_bf16 v[138:141], v[138:141], v[30:33], v[186:189]
	v_mfma_f32_16x16x32_bf16 v[158:161], v[142:145], v[14:17], v[158:161]
	v_mfma_f32_16x16x32_bf16 v[142:145], v[142:145], v[30:33], v[206:209]
	s_cbranch_vccnz .LBB0_1031
	v_max_f32_e32 v186, v149, v149
	v_max_f32_e32 v187, v148, v148
	v_max_f32_e32 v186, v187, v186
	v_max_f32_e32 v187, v153, v153
	v_max_f32_e32 v188, v152, v152
	v_max_f32_e32 v187, v188, v187
	v_max3_f32 v186, v146, v147, v186
	v_max3_f32 v187, v150, v151, v187
	v_max3_f32 v186, v186, s88, v187
	v_max_f32_e32 v187, v157, v157
	v_max_f32_e32 v188, v156, v156
	v_max_f32_e32 v187, v188, v187
	v_max_f32_e32 v188, v161, v161
	v_max_f32_e32 v189, v160, v160
	v_max_f32_e32 v188, v189, v188
	v_max3_f32 v187, v154, v155, v187
	v_max3_f32 v188, v158, v159, v188
	v_max3_f32 v202, v186, v187, v188
	v_cmp_eq_u32_e32 vcc, 0, v201
	v_mov_b32_e32 v203, 0x7f800000
	s_nop 1
	v_cndmask_b32_e32 v203, v203, v228, vcc
	v_min_f32_e32 v202, v202, v203
	s_mov_b64 s[38:39], 0
